# SB key loop: the P.V product deferred by waves 4-7 is issued under the stop-flag read latency instead of after it (on top of hand-over trim)
# baseline (speedup 1.0000x reference)
.LBB0_364:
	s_and_b32 s90, s86, 8
	s_xor_b32 s82, s90, 8
	s_lshl_b32 s82, s82, 2
	s_add_i32 s82, s82, 0
	s_add_i32 s82, s82, 0x241c0
	v_mov_b32_e32 v82, s82
	ds_read_b128 v[136:139], v82
	ds_read_b128 v[140:143], v82 offset:16
	s_andn2_b64 vcc, exec, s[72:73]
	s_cbranch_vccnz .Lsb_nopend
	v_mfma_f32_32x32x16_bf16 v[18:33], v[34:37], v[66:69], v[18:33]
	v_mfma_f32_32x32x16_bf16 v[2:17], v[38:41], v[66:69], v[2:17]
	v_mfma_f32_32x32x16_bf16 v[18:33], v[42:45], v[70:73], v[18:33]
	v_mfma_f32_32x32x16_bf16 v[2:17], v[46:49], v[70:73], v[2:17]
	v_mfma_f32_32x32x16_bf16 v[18:33], v[50:53], v[74:77], v[18:33]
	v_mfma_f32_32x32x16_bf16 v[2:17], v[54:57], v[74:77], v[2:17]
	v_mfma_f32_32x32x16_bf16 v[18:33], v[58:61], v[78:81], v[18:33]
	v_mfma_f32_32x32x16_bf16 v[2:17], v[62:65], v[78:81], v[2:17]
	s_mov_b64 s[72:73], 0
.Lsb_nopend:
	s_waitcnt lgkmcnt(0)
	v_and_b32_e32 v136, v136, v137
	v_and_b32_e32 v138, v138, v139
	v_and_b32_e32 v140, v140, v141
	v_and_b32_e32 v142, v142, v143
	v_and_b32_e32 v136, v136, v138
	v_and_b32_e32 v140, v140, v142
	v_and_b32_e32 v82, v136, v140
	v_cmp_ne_u32_e64 s[82:83], 0, v82
	s_and_b64 vcc, exec, s[82:83]
	s_cbranch_vccnz .LBB0_355
	s_cmp_lt_i32 s84, 3
	s_cbranch_scc0 .LBB0_373
	s_andn2_b64 vcc, exec, s[72:73]
	s_cbranch_vccz .LBB0_374
